# added on the static-priority version: K-loop heads aligned to 64 bytes
# speedup vs baseline: 1.0101x; 1.0054x over previous
.Lsprio_0:
	.p2align 6
